# w_out transposes moved from phase 0's static loop (8 -> 7 rounds) to the tail of the phase-2 queue (S5 workgroups' idle time); on top of S5 wave-specialised pipeline
# speedup vs baseline: 1.0237x; 1.0206x over previous
.LBB0_33:
	s_or_b64 exec, exec, s[4:5]
	v_writelane_b32 v252, s60, 8
	s_cmpk_gt_i32 s2, 0xe2f
	v_and_b32_e32 v161, 63, v162
	v_writelane_b32 v252, s61, 9
	v_writelane_b32 v252, s62, 10
	v_writelane_b32 v252, s63, 11
	v_writelane_b32 v252, s64, 12
	v_writelane_b32 v252, s65, 13
	v_writelane_b32 v252, s66, 14
	v_writelane_b32 v252, s67, 15
	v_writelane_b32 v252, s68, 16
	v_writelane_b32 v252, s69, 17
	v_writelane_b32 v252, s70, 18
	v_writelane_b32 v252, s71, 19
	v_writelane_b32 v252, s72, 20
	v_writelane_b32 v252, s73, 21
	v_lshrrev_b32_e32 v160, 6, v162
	v_lshrrev_b32_e32 v228, 5, v162
	v_lshlrev_b32_e32 v229, 2, v162
	v_mbcnt_lo_u32_b32 v230, -1, 0
	v_writelane_b32 v252, s74, 22
	v_writelane_b32 v252, s75, 23
	s_cbranch_scc1 .LBB0_59
	s_load_dword s11, s[0:1], 0x1b8
	s_waitcnt lgkmcnt(0)
	s_load_dwordx16 s[12:27], s[0:1], 0xc0
	v_lshlrev_b32_e32 v1, 2, v162
	v_mov_b32_e32 v167, 0
	v_and_b32_e32 v166, 0x7c, v1
	s_movk_i32 s4, 0x84
	s_waitcnt lgkmcnt(0)
	v_lshl_add_u64 v[170:171], s[16:17], 0, v[166:167]
	s_load_dwordx8 s[16:23], s[0:1], 0x180
	v_lshl_add_u64 v[174:175], s[12:13], 0, v[166:167]
	v_lshlrev_b32_e32 v0, 2, v161
	v_lshlrev_b32_e32 v168, 4, v161
	v_mul_u32_u24_e32 v1, 0x74, v161
	s_waitcnt lgkmcnt(0)
	s_mov_b64 s[58:59], s[22:23]
	s_mov_b64 s[56:57], s[20:21]
	s_mov_b64 s[54:55], s[18:19]
	s_mov_b64 s[52:53], s[16:17]
	s_load_dwordx16 s[12:27], s[0:1], 0x80
	v_lshlrev_b32_e32 v2, 2, v160
	v_mad_u32_u24 v231, v228, s4, v166
	s_lshl_b32 s4, s2, 3
	v_mbcnt_hi_u32_b32 v232, -1, v230
	s_waitcnt lgkmcnt(0)
	v_lshl_add_u64 v[178:179], s[24:25], 0, v[166:167]
	v_lshl_add_u64 v[182:183], s[14:15], 0, v[166:167]
	s_load_dwordx16 s[12:27], s[0:1], 0x140
	v_add3_u32 v163, v168, v1, v2
	v_lshlrev_b32_e32 v2, 1, v161
	v_mov_b32_e32 v3, v167
	v_lshl_add_u64 v[186:187], s[36:37], 0, v[166:167]
	v_mov_b32_e32 v169, v167
	v_lshlrev_b32_e32 v166, 3, v161
	s_waitcnt lgkmcnt(0)
	s_add_i32 s12, s4, 0x7ffff000
	s_lshl_b32 s4, s2, 4
	v_lshlrev_b32_e32 v194, 2, v0
	v_and_b32_e32 v0, 64, v232
	v_lshl_add_u64 v[172:173], s[56:57], 0, v[2:3]
	v_lshl_add_u64 v[176:177], s[54:55], 0, v[2:3]
	v_lshl_add_u64 v[180:181], s[52:53], 0, v[2:3]
	v_lshl_add_u64 v[184:185], s[26:27], 0, v[2:3]
	v_lshl_add_u64 v[188:189], s[24:25], 0, v[2:3]
	v_lshl_add_u64 v[190:191], s[74:75], 0, v[168:169]
	v_readfirstlane_b32 s98, v160
	s_nop 3
	s_lshl_b32 s98, s98, 12
	s_add_u32 s98, s98, 0xb000
	s_mov_b32 m0, s98
	v_lshl_add_u32 v250, v161, 4, s98
	global_load_lds_dwordx4 v[190:191], off
	global_load_lds_dwordx4 v[190:191], off offset:1024
	global_load_lds_dwordx4 v[190:191], off offset:2048
	global_load_lds_dwordx4 v[190:191], off offset:3072
	v_lshl_add_u64 v[192:193], s[58:59], 0, v[166:167]
	s_add_i32 s13, s4, 0x7fffec00
	v_mov_b32_e32 v169, 0x358637bd
	v_add_u32_e32 v233, 64, v0
	v_xor_b32_e32 v234, 32, v232
	v_xor_b32_e32 v235, 16, v232
	v_xor_b32_e32 v236, 8, v232
	v_xor_b32_e32 v237, 4, v232
	v_xor_b32_e32 v238, 2, v232
	v_xor_b32_e32 v239, 1, v232
	s_lshl_b32 s14, s11, 3
	s_lshl_b32 s15, s11, 8
	s_lshl_b32 s16, s11, 4
	s_movk_i32 s17, 0x4000
	s_mov_b32 s18, 0x800000
	s_mov_b32 s19, 0x10000
	s_mov_b32 s20, 0x28000
	s_mov_b32 s21, 0x50000
	s_mov_b32 s22, 0x58000
	s_mov_b32 s23, 0x78000
	s_mov_b32 s24, 0xa0000
	s_mov_b32 s25, 0xb0000
	s_mov_b32 s26, 0xc8000
	s_mov_b32 s27, 0xf0000
	s_mov_b32 s33, s2
	s_mov_b32 s7, 0
	v_cmp_eq_u32_e64 s[4:5], 0, v161
	s_mov_b32 s32, 0
	s_cmpk_lt_u32 s33, 0x180
	s_cbranch_scc1 .Lp0_noshift
	s_addk_i32 s33, 0x80
	s_add_i32 s12, s12, 0x400
	s_add_i32 s10, s10, 0x8000
	s_add_i32 s13, s13, 0x800
	s_mov_b32 s32, 1
.Lp0_noshift:
	s_branch .LBB0_36
.LBB0_35:
	s_add_i32 s33, s33, s11
	s_add_i32 s12, s12, s14
	s_add_i32 s10, s10, s15
	s_add_i32 s13, s13, s16
	s_cmp_eq_u32 s32, 0
	s_cbranch_scc0 .Lp0_shifted
	s_addk_i32 s33, 0x80
	s_add_i32 s12, s12, 0x400
	s_add_i32 s10, s10, 0x8000
	s_add_i32 s13, s13, 0x800
	s_mov_b32 s32, 1
.Lp0_shifted:
	s_cmpk_lt_i32 s33, 0xe30
	s_cbranch_scc0 .LBB0_59

.LBB0_196:
	s_or_b64 exec, exec, s[0:1]
	s_waitcnt lgkmcnt(0)
	s_barrier
	ds_read_b32 v0, v194
	s_movk_i32 s0, 0x5ff
	s_waitcnt lgkmcnt(0)
	v_cmp_lt_i32_e32 vcc, s0, v0
	v_readfirstlane_b32 s36, v0
	s_mov_b64 s[0:1], -1
	s_cbranch_vccnz .LBB0_191
	s_cmpk_gt_i32 s36, 0xff
	s_cbranch_scc0 .LBB0_316
	s_cmpk_gt_u32 s36, 0x4ff
	s_cbranch_scc0 .LBB0_212
	s_cmpk_gt_u32 s36, 0x57f
	s_cbranch_scc1 .Lp2_tr
	v_readlane_b32 s12, v252, 30
	v_readlane_b32 s13, v252, 31
	s_barrier
	s_and_saveexec_b64 s[0:1], s[12:13]
	v_readlane_b32 s68, v251, 8
	v_readlane_b32 s78, v251, 18
	v_readlane_b32 s79, v251, 19
	v_readlane_b32 s69, v251, 9
	v_readlane_b32 s70, v251, 10
	v_readlane_b32 s71, v251, 11
	v_readlane_b32 s72, v251, 12
	v_readlane_b32 s73, v251, 13
	v_readlane_b32 s74, v251, 14
	v_readlane_b32 s75, v251, 15
	v_readlane_b32 s76, v251, 16
	v_readlane_b32 s77, v251, 17
	v_readlane_b32 s80, v251, 20
	v_readlane_b32 s81, v251, 21
	v_readlane_b32 s82, v251, 22
	v_readlane_b32 s83, v251, 23
	s_cbranch_execz .LBB0_202
	s_mov_b64 s[14:15], 0
	v_mov_b32_e32 v2, v229
	v_mov_b32_e32 v3, v103

.Lp2_tr:
	s_sub_u32 s12, s36, 0x580
	s_lshr_b32 s13, s12, 2
	s_lshl_b32 s13, s13, 5
	s_and_b32 s14, s12, 3
	s_lshl_b32 s14, s14, 8
	s_mov_b32 s16, 0x1000
	s_mov_b32 s17, 0x800
	v_readlane_b32 s70, v251, 36
	v_readlane_b32 s71, v251, 37
	v_readlane_b32 s72, v251, 0
	v_readlane_b32 s73, v251, 1
	s_mul_i32 s18, s14, s16
	s_lshl_b32 s19, s13, 2
	s_add_u32 s18, s18, s19
	s_add_u32 s70, s70, s18
	s_addc_u32 s71, s71, 0
	s_mul_i32 s18, s13, s17
	s_lshl_b32 s19, s14, 1
	s_add_u32 s18, s18, s19
	s_add_u32 s72, s72, s18
	s_addc_u32 s73, s73, 0
	s_lshl_b32 s74, s16, 3
	s_lshl_b32 s75, s17, 2
	v_and_b32_e32 v176, 31, v162
	v_lshrrev_b32_e32 v177, 5, v162
	v_lshlrev_b32_e32 v178, 2, v176
	v_mad_u32_u24 v178, v177, s16, v178
	v_mul_u32_u24_e32 v179, 33, v177
	v_add_lshl_u32 v179, v179, v176, 2
	v_and_b32_e32 v180, 63, v162
	v_lshrrev_b32_e32 v181, 6, v162
	v_mul_u32_u24_e32 v182, 33, v180
	v_add_lshl_u32 v182, v182, v181, 2
	v_lshlrev_b32_e32 v183, 1, v180
	v_mad_u32_u24 v183, v181, s17, v183
	s_waitcnt lgkmcnt(0)
	s_barrier
	s_mov_b64 s[76:77], s[70:71]
	global_load_dword v40, v178, s[76:77]
	s_add_u32 s76, s76, s74
	s_addc_u32 s77, s77, 0
	global_load_dword v41, v178, s[76:77]
	s_add_u32 s76, s76, s74
	s_addc_u32 s77, s77, 0
	global_load_dword v42, v178, s[76:77]
	s_add_u32 s76, s76, s74
	s_addc_u32 s77, s77, 0
	global_load_dword v43, v178, s[76:77]
	s_add_u32 s76, s76, s74
	s_addc_u32 s77, s77, 0
	global_load_dword v44, v178, s[76:77]
	s_add_u32 s76, s76, s74
	s_addc_u32 s77, s77, 0
	global_load_dword v45, v178, s[76:77]
	s_add_u32 s76, s76, s74
	s_addc_u32 s77, s77, 0
	global_load_dword v46, v178, s[76:77]
	s_add_u32 s76, s76, s74
	s_addc_u32 s77, s77, 0
	global_load_dword v47, v178, s[76:77]
	s_add_u32 s76, s76, s74
	s_addc_u32 s77, s77, 0
	global_load_dword v48, v178, s[76:77]
	s_add_u32 s76, s76, s74
	s_addc_u32 s77, s77, 0
	global_load_dword v49, v178, s[76:77]
	s_add_u32 s76, s76, s74
	s_addc_u32 s77, s77, 0
	global_load_dword v50, v178, s[76:77]
	s_add_u32 s76, s76, s74
	s_addc_u32 s77, s77, 0
	global_load_dword v51, v178, s[76:77]
	s_add_u32 s76, s76, s74
	s_addc_u32 s77, s77, 0
	global_load_dword v52, v178, s[76:77]
	s_add_u32 s76, s76, s74
	s_addc_u32 s77, s77, 0
	global_load_dword v53, v178, s[76:77]
	s_add_u32 s76, s76, s74
	s_addc_u32 s77, s77, 0
	global_load_dword v54, v178, s[76:77]
	s_add_u32 s76, s76, s74
	s_addc_u32 s77, s77, 0
	global_load_dword v55, v178, s[76:77]
	s_add_u32 s76, s76, s74
	s_addc_u32 s77, s77, 0
	global_load_dword v56, v178, s[76:77]
	s_add_u32 s76, s76, s74
	s_addc_u32 s77, s77, 0
	global_load_dword v57, v178, s[76:77]
	s_add_u32 s76, s76, s74
	s_addc_u32 s77, s77, 0
	global_load_dword v58, v178, s[76:77]
	s_add_u32 s76, s76, s74
	s_addc_u32 s77, s77, 0
	global_load_dword v59, v178, s[76:77]
	s_add_u32 s76, s76, s74
	s_addc_u32 s77, s77, 0
	global_load_dword v60, v178, s[76:77]
	s_add_u32 s76, s76, s74
	s_addc_u32 s77, s77, 0
	global_load_dword v61, v178, s[76:77]
	s_add_u32 s76, s76, s74
	s_addc_u32 s77, s77, 0
	global_load_dword v62, v178, s[76:77]
	s_add_u32 s76, s76, s74
	s_addc_u32 s77, s77, 0
	global_load_dword v63, v178, s[76:77]
	s_add_u32 s76, s76, s74
	s_addc_u32 s77, s77, 0
	global_load_dword v64, v178, s[76:77]
	s_add_u32 s76, s76, s74
	s_addc_u32 s77, s77, 0
	global_load_dword v65, v178, s[76:77]
	s_add_u32 s76, s76, s74
	s_addc_u32 s77, s77, 0
	global_load_dword v66, v178, s[76:77]
	s_add_u32 s76, s76, s74
	s_addc_u32 s77, s77, 0
	global_load_dword v124, v178, s[76:77]
	s_add_u32 s76, s76, s74
	s_addc_u32 s77, s77, 0
	global_load_dword v125, v178, s[76:77]
	s_add_u32 s76, s76, s74
	s_addc_u32 s77, s77, 0
	global_load_dword v126, v178, s[76:77]
	s_add_u32 s76, s76, s74
	s_addc_u32 s77, s77, 0
	global_load_dword v127, v178, s[76:77]
	s_add_u32 s76, s76, s74
	s_addc_u32 s77, s77, 0
	global_load_dword v128, v178, s[76:77]
	s_waitcnt vmcnt(31)
	ds_write_b32 v179, v40 offset:0
	s_waitcnt vmcnt(30)
	ds_write_b32 v179, v41 offset:1056
	s_waitcnt vmcnt(29)
	ds_write_b32 v179, v42 offset:2112
	s_waitcnt vmcnt(28)
	ds_write_b32 v179, v43 offset:3168
	s_waitcnt vmcnt(27)
	ds_write_b32 v179, v44 offset:4224
	s_waitcnt vmcnt(26)
	ds_write_b32 v179, v45 offset:5280
	s_waitcnt vmcnt(25)
	ds_write_b32 v179, v46 offset:6336
	s_waitcnt vmcnt(24)
	ds_write_b32 v179, v47 offset:7392
	s_waitcnt lgkmcnt(0)
	s_barrier
	ds_read_b32 v168, v182 offset:0
	ds_read_b32 v169, v182 offset:16
	ds_read_b32 v170, v182 offset:32
	ds_read_b32 v171, v182 offset:48
	ds_read_b32 v172, v182 offset:64
	ds_read_b32 v173, v182 offset:80
	ds_read_b32 v174, v182 offset:96
	ds_read_b32 v175, v182 offset:112
	s_mov_b64 s[78:79], s[72:73]
	s_waitcnt lgkmcnt(7)
	v_cvt_pk_bf16_f32 v168, v168, v168
	global_store_short v183, v168, s[78:79] offset:0
	s_add_u32 s78, s78, s75
	s_addc_u32 s79, s79, 0
	s_waitcnt lgkmcnt(6)
	v_cvt_pk_bf16_f32 v169, v169, v169
	global_store_short v183, v169, s[78:79] offset:0
	s_add_u32 s78, s78, s75
	s_addc_u32 s79, s79, 0
	s_waitcnt lgkmcnt(5)
	v_cvt_pk_bf16_f32 v170, v170, v170
	global_store_short v183, v170, s[78:79] offset:0
	s_add_u32 s78, s78, s75
	s_addc_u32 s79, s79, 0
	s_waitcnt lgkmcnt(4)
	v_cvt_pk_bf16_f32 v171, v171, v171
	global_store_short v183, v171, s[78:79] offset:0
	s_add_u32 s78, s78, s75
	s_addc_u32 s79, s79, 0
	s_waitcnt lgkmcnt(3)
	v_cvt_pk_bf16_f32 v172, v172, v172
	global_store_short v183, v172, s[78:79] offset:0
	s_add_u32 s78, s78, s75
	s_addc_u32 s79, s79, 0
	s_waitcnt lgkmcnt(2)
	v_cvt_pk_bf16_f32 v173, v173, v173
	global_store_short v183, v173, s[78:79] offset:0
	s_add_u32 s78, s78, s75
	s_addc_u32 s79, s79, 0
	s_waitcnt lgkmcnt(1)
	v_cvt_pk_bf16_f32 v174, v174, v174
	global_store_short v183, v174, s[78:79] offset:0
	s_add_u32 s78, s78, s75
	s_addc_u32 s79, s79, 0
	s_waitcnt lgkmcnt(0)
	v_cvt_pk_bf16_f32 v175, v175, v175
	global_store_short v183, v175, s[78:79] offset:0
	s_barrier
	s_waitcnt vmcnt(31)
	ds_write_b32 v179, v48 offset:0
	s_waitcnt vmcnt(30)
	ds_write_b32 v179, v49 offset:1056
	s_waitcnt vmcnt(29)
	ds_write_b32 v179, v50 offset:2112
	s_waitcnt vmcnt(28)
	ds_write_b32 v179, v51 offset:3168
	s_waitcnt vmcnt(27)
	ds_write_b32 v179, v52 offset:4224
	s_waitcnt vmcnt(26)
	ds_write_b32 v179, v53 offset:5280
	s_waitcnt vmcnt(25)
	ds_write_b32 v179, v54 offset:6336
	s_waitcnt vmcnt(24)
	ds_write_b32 v179, v55 offset:7392
	s_waitcnt lgkmcnt(0)
	s_barrier
	ds_read_b32 v168, v182 offset:0
	ds_read_b32 v169, v182 offset:16
	ds_read_b32 v170, v182 offset:32
	ds_read_b32 v171, v182 offset:48
	ds_read_b32 v172, v182 offset:64
	ds_read_b32 v173, v182 offset:80
	ds_read_b32 v174, v182 offset:96
	ds_read_b32 v175, v182 offset:112
	s_mov_b64 s[78:79], s[72:73]
	s_waitcnt lgkmcnt(7)
	v_cvt_pk_bf16_f32 v168, v168, v168
	global_store_short v183, v168, s[78:79] offset:128
	s_add_u32 s78, s78, s75
	s_addc_u32 s79, s79, 0
	s_waitcnt lgkmcnt(6)
	v_cvt_pk_bf16_f32 v169, v169, v169
	global_store_short v183, v169, s[78:79] offset:128
	s_add_u32 s78, s78, s75
	s_addc_u32 s79, s79, 0
	s_waitcnt lgkmcnt(5)
	v_cvt_pk_bf16_f32 v170, v170, v170
	global_store_short v183, v170, s[78:79] offset:128
	s_add_u32 s78, s78, s75
	s_addc_u32 s79, s79, 0
	s_waitcnt lgkmcnt(4)
	v_cvt_pk_bf16_f32 v171, v171, v171
	global_store_short v183, v171, s[78:79] offset:128
	s_add_u32 s78, s78, s75
	s_addc_u32 s79, s79, 0
	s_waitcnt lgkmcnt(3)
	v_cvt_pk_bf16_f32 v172, v172, v172
	global_store_short v183, v172, s[78:79] offset:128
	s_add_u32 s78, s78, s75
	s_addc_u32 s79, s79, 0
	s_waitcnt lgkmcnt(2)
	v_cvt_pk_bf16_f32 v173, v173, v173
	global_store_short v183, v173, s[78:79] offset:128
	s_add_u32 s78, s78, s75
	s_addc_u32 s79, s79, 0
	s_waitcnt lgkmcnt(1)
	v_cvt_pk_bf16_f32 v174, v174, v174
	global_store_short v183, v174, s[78:79] offset:128
	s_add_u32 s78, s78, s75
	s_addc_u32 s79, s79, 0
	s_waitcnt lgkmcnt(0)
	v_cvt_pk_bf16_f32 v175, v175, v175
	global_store_short v183, v175, s[78:79] offset:128
	s_barrier
	s_waitcnt vmcnt(31)
	ds_write_b32 v179, v56 offset:0
	s_waitcnt vmcnt(30)
	ds_write_b32 v179, v57 offset:1056
	s_waitcnt vmcnt(29)
	ds_write_b32 v179, v58 offset:2112
	s_waitcnt vmcnt(28)
	ds_write_b32 v179, v59 offset:3168
	s_waitcnt vmcnt(27)
	ds_write_b32 v179, v60 offset:4224
	s_waitcnt vmcnt(26)
	ds_write_b32 v179, v61 offset:5280
	s_waitcnt vmcnt(25)
	ds_write_b32 v179, v62 offset:6336
	s_waitcnt vmcnt(24)
	ds_write_b32 v179, v63 offset:7392
	s_waitcnt lgkmcnt(0)
	s_barrier
	ds_read_b32 v168, v182 offset:0
	ds_read_b32 v169, v182 offset:16
	ds_read_b32 v170, v182 offset:32
	ds_read_b32 v171, v182 offset:48
	ds_read_b32 v172, v182 offset:64
	ds_read_b32 v173, v182 offset:80
	ds_read_b32 v174, v182 offset:96
	ds_read_b32 v175, v182 offset:112
	s_mov_b64 s[78:79], s[72:73]
	s_waitcnt lgkmcnt(7)
	v_cvt_pk_bf16_f32 v168, v168, v168
	global_store_short v183, v168, s[78:79] offset:256
	s_add_u32 s78, s78, s75
	s_addc_u32 s79, s79, 0
	s_waitcnt lgkmcnt(6)
	v_cvt_pk_bf16_f32 v169, v169, v169
	global_store_short v183, v169, s[78:79] offset:256
	s_add_u32 s78, s78, s75
	s_addc_u32 s79, s79, 0
	s_waitcnt lgkmcnt(5)
	v_cvt_pk_bf16_f32 v170, v170, v170
	global_store_short v183, v170, s[78:79] offset:256
	s_add_u32 s78, s78, s75
	s_addc_u32 s79, s79, 0
	s_waitcnt lgkmcnt(4)
	v_cvt_pk_bf16_f32 v171, v171, v171
	global_store_short v183, v171, s[78:79] offset:256
	s_add_u32 s78, s78, s75
	s_addc_u32 s79, s79, 0
	s_waitcnt lgkmcnt(3)
	v_cvt_pk_bf16_f32 v172, v172, v172
	global_store_short v183, v172, s[78:79] offset:256
	s_add_u32 s78, s78, s75
	s_addc_u32 s79, s79, 0
	s_waitcnt lgkmcnt(2)
	v_cvt_pk_bf16_f32 v173, v173, v173
	global_store_short v183, v173, s[78:79] offset:256
	s_add_u32 s78, s78, s75
	s_addc_u32 s79, s79, 0
	s_waitcnt lgkmcnt(1)
	v_cvt_pk_bf16_f32 v174, v174, v174
	global_store_short v183, v174, s[78:79] offset:256
	s_add_u32 s78, s78, s75
	s_addc_u32 s79, s79, 0
	s_waitcnt lgkmcnt(0)
	v_cvt_pk_bf16_f32 v175, v175, v175
	global_store_short v183, v175, s[78:79] offset:256
	s_barrier
	s_waitcnt vmcnt(31)
	ds_write_b32 v179, v64 offset:0
	s_waitcnt vmcnt(30)
	ds_write_b32 v179, v65 offset:1056
	s_waitcnt vmcnt(29)
	ds_write_b32 v179, v66 offset:2112
	s_waitcnt vmcnt(28)
	ds_write_b32 v179, v124 offset:3168
	s_waitcnt vmcnt(27)
	ds_write_b32 v179, v125 offset:4224
	s_waitcnt vmcnt(26)
	ds_write_b32 v179, v126 offset:5280
	s_waitcnt vmcnt(25)
	ds_write_b32 v179, v127 offset:6336
	s_waitcnt vmcnt(24)
	ds_write_b32 v179, v128 offset:7392
	s_waitcnt lgkmcnt(0)
	s_barrier
	ds_read_b32 v168, v182 offset:0
	ds_read_b32 v169, v182 offset:16
	ds_read_b32 v170, v182 offset:32
	ds_read_b32 v171, v182 offset:48
	ds_read_b32 v172, v182 offset:64
	ds_read_b32 v173, v182 offset:80
	ds_read_b32 v174, v182 offset:96
	ds_read_b32 v175, v182 offset:112
	s_mov_b64 s[78:79], s[72:73]
	s_waitcnt lgkmcnt(7)
	v_cvt_pk_bf16_f32 v168, v168, v168
	global_store_short v183, v168, s[78:79] offset:384
	s_add_u32 s78, s78, s75
	s_addc_u32 s79, s79, 0
	s_waitcnt lgkmcnt(6)
	v_cvt_pk_bf16_f32 v169, v169, v169
	global_store_short v183, v169, s[78:79] offset:384
	s_add_u32 s78, s78, s75
	s_addc_u32 s79, s79, 0
	s_waitcnt lgkmcnt(5)
	v_cvt_pk_bf16_f32 v170, v170, v170
	global_store_short v183, v170, s[78:79] offset:384
	s_add_u32 s78, s78, s75
	s_addc_u32 s79, s79, 0
	s_waitcnt lgkmcnt(4)
	v_cvt_pk_bf16_f32 v171, v171, v171
	global_store_short v183, v171, s[78:79] offset:384
	s_add_u32 s78, s78, s75
	s_addc_u32 s79, s79, 0
	s_waitcnt lgkmcnt(3)
	v_cvt_pk_bf16_f32 v172, v172, v172
	global_store_short v183, v172, s[78:79] offset:384
	s_add_u32 s78, s78, s75
	s_addc_u32 s79, s79, 0
	s_waitcnt lgkmcnt(2)
	v_cvt_pk_bf16_f32 v173, v173, v173
	global_store_short v183, v173, s[78:79] offset:384
	s_add_u32 s78, s78, s75
	s_addc_u32 s79, s79, 0
	s_waitcnt lgkmcnt(1)
	v_cvt_pk_bf16_f32 v174, v174, v174
	global_store_short v183, v174, s[78:79] offset:384
	s_add_u32 s78, s78, s75
	s_addc_u32 s79, s79, 0
	s_waitcnt lgkmcnt(0)
	v_cvt_pk_bf16_f32 v175, v175, v175
	global_store_short v183, v175, s[78:79] offset:384
	s_barrier
	s_branch .LBB0_190
